# head epilogue: reuse 1/sqrt of the first half-head for the second when the head class has one 64-wide norm (s1==s0), instead of recomputing it
# speedup vs baseline: 1.0499x; 1.0028x over previous
;     __device__ __forceinline__ static float xsh(float v, int mask, int lane) { return __builtin_bit_cast(float, __builtin_amdgcn_ds_bpermute((lane ^ mask) << 2, __builtin_bit_cast(int, v))); }
;     __device__ __forceinline__ void head_epilogue(const f32x4 (&acc)[2][2][4][2], const Unit& u, int wr, int wc, int fr, int fq) const {
;     ...
;                     if (cls != 3) { s0 += s1; s0 += xsh(s0, 16, lane); s0 += xsh(s0, 32, lane); s0 = s0 * (1.f / 64.f); s1 = s0; }
;                     else { s0 += xsh(s0, 16, lane); s0 += xsh(s0, 32, lane); s1 += xsh(s1, 16, lane); s1 += xsh(s1, 32, lane); s0 *= (1.f / 32.f); s1 *= (1.f / 32.f); }
;                     const float r0 = 1.f / sqrtf(s0 + 1e-6f), r1 = 1.f / sqrtf(s1 + 1e-6f);
; #pragma unroll
;                     for (int n = 0; n < 2; ++n) { v[0][n] = v[0][n] * r0 * gv[0][n]; v[1][n] = v[1][n] * r1 * gv[1][n]; }
.LBB0_551:
	s_nop 0
	v_add_f32_e32 v0, 0x358637bd, v3
	v_cmp_gt_f32_e32 vcc, s64, v0
	v_mul_f32_e32 v3, 0x4f800000, v0
	v_add_f32_e32 v2, 0x358637bd, v2
	v_cndmask_b32_e32 v0, v0, v3, vcc
	v_sqrt_f32_e32 v3, v0
	s_nop 0
	v_add_u32_e32 v4, -1, v3
	v_fma_f32 v5, -v4, v3, v0
	v_cmp_ge_f32_e64 s[10:11], 0, v5
	v_add_u32_e32 v5, 1, v3
	s_nop 0
	v_cndmask_b32_e64 v4, v3, v4, s[10:11]
	v_fma_f32 v3, -v5, v3, v0
	v_cmp_lt_f32_e64 s[10:11], 0, v3
	s_nop 1
	v_cndmask_b32_e64 v3, v4, v5, s[10:11]
	v_mul_f32_e32 v4, 0x37800000, v3
	v_cndmask_b32_e32 v3, v3, v4, vcc
	v_cmp_class_f32_e32 vcc, v0, v186
	s_nop 1
	v_cndmask_b32_e32 v0, v3, v0, vcc
	v_div_scale_f32 v3, s[10:11], v0, v0, 1.0
	v_rcp_f32_e32 v4, v3
	s_nop 0
	v_fma_f32 v5, -v3, v4, 1.0
	v_fmac_f32_e32 v4, v5, v4
	v_div_scale_f32 v5, vcc, 1.0, v0, 1.0
	v_mul_f32_e32 v6, v5, v4
	v_fma_f32 v7, -v3, v6, v5
	v_fmac_f32_e32 v6, v7, v4
	v_fma_f32 v3, -v3, v6, v5
	v_div_fmas_f32 v3, v3, v4, v6
	v_div_fixup_f32 v0, v3, v0, 1.0
	s_and_b64 vcc, exec, s[12:13]
	s_cbranch_vccnz .Lhd_two_0
	v_mov_b32_e32 v10, v0
	s_branch .Lhd_one_0
.Lhd_two_0:
	v_cmp_gt_f32_e32 vcc, s64, v2
	v_mul_f32_e32 v3, 0x4f800000, v2
	s_nop 0
	v_cndmask_b32_e32 v2, v2, v3, vcc
	v_sqrt_f32_e32 v3, v2
	s_nop 0
	v_add_u32_e32 v4, -1, v3
	v_fma_f32 v5, -v4, v3, v2
	v_cmp_ge_f32_e64 s[10:11], 0, v5
	v_add_u32_e32 v5, 1, v3
	s_nop 0
	v_cndmask_b32_e64 v4, v3, v4, s[10:11]
	v_fma_f32 v3, -v5, v3, v2
	v_cmp_lt_f32_e64 s[10:11], 0, v3
	s_nop 1
	v_cndmask_b32_e64 v3, v4, v5, s[10:11]
	v_mul_f32_e32 v4, 0x37800000, v3
	v_cndmask_b32_e32 v3, v3, v4, vcc
	v_cmp_class_f32_e32 vcc, v2, v186
	s_nop 1
	v_cndmask_b32_e32 v2, v3, v2, vcc
	v_div_scale_f32 v3, s[10:11], v2, v2, 1.0
	v_rcp_f32_e32 v4, v3
	s_nop 0
	v_fma_f32 v5, -v3, v4, 1.0
	v_fmac_f32_e32 v4, v5, v4
	v_div_scale_f32 v5, vcc, 1.0, v2, 1.0
	v_mul_f32_e32 v6, v5, v4
	v_fma_f32 v7, -v3, v6, v5
	v_fmac_f32_e32 v6, v7, v4
	v_fma_f32 v3, -v3, v6, v5
	v_div_fmas_f32 v3, v3, v4, v6
	v_div_fixup_f32 v10, v3, v2, 1.0
.Lhd_one_0:
	v_pk_mul_f32 v[6:7], v[150:151], v[10:11] op_sel_hi:[1,0]
	v_pk_mul_f32 v[8:9], v[152:153], v[10:11] op_sel_hi:[1,0]
	v_pk_mul_f32 v[2:3], v[154:155], v[0:1] op_sel_hi:[1,0]
	v_pk_mul_f32 v[4:5], v[156:157], v[0:1] op_sel_hi:[1,0]
	s_waitcnt vmcnt(0)
	v_pk_mul_f32 v[164:165], v[28:29], v[8:9]
	v_pk_mul_f32 v[162:163], v[26:27], v[6:7]
	v_pk_mul_f32 v[6:7], v[158:159], v[0:1] op_sel_hi:[1,0]
	v_pk_mul_f32 v[8:9], v[160:161], v[0:1] op_sel_hi:[1,0]
	v_pk_mul_f32 v[12:13], v[146:147], v[10:11] op_sel_hi:[1,0]
	v_pk_mul_f32 v[10:11], v[148:149], v[10:11] op_sel_hi:[1,0]
	v_pk_mul_f32 v[4:5], v[32:33], v[4:5]
	v_pk_mul_f32 v[2:3], v[30:31], v[2:3]
	v_pk_mul_f32 v[8:9], v[24:25], v[8:9]
	v_pk_mul_f32 v[6:7], v[22:23], v[6:7]
	v_pk_mul_f32 v[168:169], v[20:21], v[10:11]
	v_pk_mul_f32 v[166:167], v[18:19], v[12:13]
	s_andn2_b64 vcc, exec, s[58:59]
	s_cbranch_vccz .LBB0_555
	s_andn2_b64 vcc, exec, s[74:75]
	s_cbranch_vccz .LBB0_556

;     __device__ __forceinline__ static float xsh(float v, int mask, int lane) { return __builtin_bit_cast(float, __builtin_amdgcn_ds_bpermute((lane ^ mask) << 2, __builtin_bit_cast(int, v))); }
;     __device__ __forceinline__ void head_epilogue(const f32x4 (&acc)[2][2][4][2], const Unit& u, int wr, int wc, int fr, int fq) const {
;     ...
;                     if (cls != 3) { s0 += s1; s0 += xsh(s0, 16, lane); s0 += xsh(s0, 32, lane); s0 = s0 * (1.f / 64.f); s1 = s0; }
;                     else { s0 += xsh(s0, 16, lane); s0 += xsh(s0, 32, lane); s1 += xsh(s1, 16, lane); s1 += xsh(s1, 32, lane); s0 *= (1.f / 32.f); s1 *= (1.f / 32.f); }
;                     const float r0 = 1.f / sqrtf(s0 + 1e-6f), r1 = 1.f / sqrtf(s1 + 1e-6f);
; #pragma unroll
;                     for (int n = 0; n < 2; ++n) { v[0][n] = v[0][n] * r0 * gv[0][n]; v[1][n] = v[1][n] * r1 * gv[1][n]; }
.LBB0_575:
	s_nop 0
	v_add_f32_e32 v0, 0x358637bd, v3
	s_mov_b32 s18, 0xf800000
	v_cmp_gt_f32_e32 vcc, s18, v0
	v_mul_f32_e32 v3, 0x4f800000, v0
	v_add_f32_e32 v2, 0x358637bd, v2
	v_cndmask_b32_e32 v0, v0, v3, vcc
	v_sqrt_f32_e32 v3, v0
	s_nop 0
	v_add_u32_e32 v4, -1, v3
	v_fma_f32 v5, -v4, v3, v0
	v_cmp_ge_f32_e64 s[16:17], 0, v5
	v_add_u32_e32 v5, 1, v3
	s_nop 0
	v_cndmask_b32_e64 v4, v3, v4, s[16:17]
	v_fma_f32 v3, -v5, v3, v0
	v_cmp_lt_f32_e64 s[16:17], 0, v3
	s_nop 1
	v_cndmask_b32_e64 v3, v4, v5, s[16:17]
	v_mul_f32_e32 v4, 0x37800000, v3
	v_cndmask_b32_e32 v3, v3, v4, vcc
	v_cmp_class_f32_e32 vcc, v0, v186
	s_nop 1
	v_cndmask_b32_e32 v0, v3, v0, vcc
	v_div_scale_f32 v3, s[16:17], v0, v0, 1.0
	v_rcp_f32_e32 v4, v3
	s_nop 0
	v_fma_f32 v5, -v3, v4, 1.0
	v_fmac_f32_e32 v4, v5, v4
	v_div_scale_f32 v5, vcc, 1.0, v0, 1.0
	v_mul_f32_e32 v6, v5, v4
	v_fma_f32 v7, -v3, v6, v5
	v_fmac_f32_e32 v6, v7, v4
	v_fma_f32 v3, -v3, v6, v5
	v_div_fmas_f32 v3, v3, v4, v6
	v_div_fixup_f32 v0, v3, v0, 1.0
	s_and_b64 vcc, exec, s[12:13]
	s_cbranch_vccnz .Lhd_two_1
	v_mov_b32_e32 v10, v0
	s_branch .Lhd_one_1
.Lhd_two_1:
	v_cmp_gt_f32_e32 vcc, s18, v2
	v_mul_f32_e32 v3, 0x4f800000, v2
	s_nop 0
	v_cndmask_b32_e32 v2, v2, v3, vcc
	v_sqrt_f32_e32 v3, v2
	s_nop 0
	v_add_u32_e32 v4, -1, v3
	v_fma_f32 v5, -v4, v3, v2
	v_cmp_ge_f32_e64 s[16:17], 0, v5
	v_add_u32_e32 v5, 1, v3
	s_nop 0
	v_cndmask_b32_e64 v4, v3, v4, s[16:17]
	v_fma_f32 v3, -v5, v3, v2
	v_cmp_lt_f32_e64 s[16:17], 0, v3
	s_nop 1
	v_cndmask_b32_e64 v3, v4, v5, s[16:17]
	v_mul_f32_e32 v4, 0x37800000, v3
	v_cndmask_b32_e32 v3, v3, v4, vcc
	v_cmp_class_f32_e32 vcc, v2, v186
	s_nop 1
	v_cndmask_b32_e32 v2, v3, v2, vcc
	v_div_scale_f32 v3, s[16:17], v2, v2, 1.0
	v_rcp_f32_e32 v4, v3
	s_nop 0
	v_fma_f32 v5, -v3, v4, 1.0
	v_fmac_f32_e32 v4, v5, v4
	v_div_scale_f32 v5, vcc, 1.0, v2, 1.0
	v_mul_f32_e32 v6, v5, v4
	v_fma_f32 v7, -v3, v6, v5
	v_fmac_f32_e32 v6, v7, v4
	v_fma_f32 v3, -v3, v6, v5
	v_div_fmas_f32 v3, v3, v4, v6
	v_div_fixup_f32 v10, v3, v2, 1.0
.Lhd_one_1:
	v_pk_mul_f32 v[6:7], v[134:135], v[10:11] op_sel_hi:[1,0]
	v_pk_mul_f32 v[8:9], v[136:137], v[10:11] op_sel_hi:[1,0]
	v_pk_mul_f32 v[2:3], v[142:143], v[0:1] op_sel_hi:[1,0]
	v_pk_mul_f32 v[4:5], v[144:145], v[0:1] op_sel_hi:[1,0]
	s_waitcnt vmcnt(0)
	v_pk_mul_f32 v[164:165], v[28:29], v[8:9]
	v_pk_mul_f32 v[162:163], v[26:27], v[6:7]
	v_pk_mul_f32 v[6:7], v[138:139], v[0:1] op_sel_hi:[1,0]
	v_pk_mul_f32 v[8:9], v[140:141], v[0:1] op_sel_hi:[1,0]
	v_pk_mul_f32 v[12:13], v[130:131], v[10:11] op_sel_hi:[1,0]
	v_pk_mul_f32 v[10:11], v[132:133], v[10:11] op_sel_hi:[1,0]
	v_pk_mul_f32 v[4:5], v[32:33], v[4:5]
	v_pk_mul_f32 v[2:3], v[30:31], v[2:3]
	v_pk_mul_f32 v[8:9], v[24:25], v[8:9]
	v_pk_mul_f32 v[6:7], v[22:23], v[6:7]
	v_pk_mul_f32 v[168:169], v[20:21], v[10:11]
	v_pk_mul_f32 v[166:167], v[18:19], v[12:13]
	s_andn2_b64 vcc, exec, s[58:59]
	s_cbranch_vccz .LBB0_579
	s_andn2_b64 vcc, exec, s[74:75]
	s_cbranch_vccz .LBB0_580

;     __device__ __forceinline__ static float xsh(float v, int mask, int lane) { return __builtin_bit_cast(float, __builtin_amdgcn_ds_bpermute((lane ^ mask) << 2, __builtin_bit_cast(int, v))); }
;     __device__ __forceinline__ void head_epilogue(const f32x4 (&acc)[2][2][4][2], const Unit& u, int wr, int wc, int fr, int fq) const {
;     ...
;                     if (cls != 3) { s0 += s1; s0 += xsh(s0, 16, lane); s0 += xsh(s0, 32, lane); s0 = s0 * (1.f / 64.f); s1 = s0; }
;                     else { s0 += xsh(s0, 16, lane); s0 += xsh(s0, 32, lane); s1 += xsh(s1, 16, lane); s1 += xsh(s1, 32, lane); s0 *= (1.f / 32.f); s1 *= (1.f / 32.f); }
;                     const float r0 = 1.f / sqrtf(s0 + 1e-6f), r1 = 1.f / sqrtf(s1 + 1e-6f);
; #pragma unroll
;                     for (int n = 0; n < 2; ++n) { v[0][n] = v[0][n] * r0 * gv[0][n]; v[1][n] = v[1][n] * r1 * gv[1][n]; }
.LBB0_589:
	s_nop 0
	v_add_f32_e32 v0, 0x358637bd, v3
	s_mov_b32 s56, 0xf800000
	v_cmp_gt_f32_e32 vcc, s56, v0
	v_mul_f32_e32 v3, 0x4f800000, v0
	v_add_f32_e32 v2, 0x358637bd, v2
	v_cndmask_b32_e32 v0, v0, v3, vcc
	v_sqrt_f32_e32 v3, v0
	s_nop 0
	v_add_u32_e32 v4, -1, v3
	v_fma_f32 v5, -v4, v3, v0
	v_cmp_ge_f32_e64 s[18:19], 0, v5
	v_add_u32_e32 v5, 1, v3
	s_nop 0
	v_cndmask_b32_e64 v4, v3, v4, s[18:19]
	v_fma_f32 v3, -v5, v3, v0
	v_cmp_lt_f32_e64 s[18:19], 0, v3
	s_nop 1
	v_cndmask_b32_e64 v3, v4, v5, s[18:19]
	v_mul_f32_e32 v4, 0x37800000, v3
	v_cndmask_b32_e32 v3, v3, v4, vcc
	v_cmp_class_f32_e32 vcc, v0, v186
	s_nop 1
	v_cndmask_b32_e32 v0, v3, v0, vcc
	v_div_scale_f32 v3, s[0:1], v0, v0, 1.0
	v_rcp_f32_e32 v4, v3
	s_nop 0
	v_fma_f32 v5, -v3, v4, 1.0
	v_fmac_f32_e32 v4, v5, v4
	v_div_scale_f32 v5, vcc, 1.0, v0, 1.0
	v_mul_f32_e32 v6, v5, v4
	v_fma_f32 v7, -v3, v6, v5
	v_fmac_f32_e32 v6, v7, v4
	v_fma_f32 v3, -v3, v6, v5
	v_div_fmas_f32 v3, v3, v4, v6
	v_div_fixup_f32 v0, v3, v0, 1.0
	s_and_b64 vcc, exec, s[12:13]
	s_cbranch_vccnz .Lhd_two_2
	v_mov_b32_e32 v10, v0
	s_branch .Lhd_one_2
.Lhd_two_2:
	v_cmp_gt_f32_e32 vcc, s56, v2
	v_mul_f32_e32 v3, 0x4f800000, v2
	s_nop 0
	v_cndmask_b32_e32 v2, v2, v3, vcc
	v_sqrt_f32_e32 v3, v2
	s_nop 0
	v_add_u32_e32 v4, -1, v3
	v_fma_f32 v5, -v4, v3, v2
	v_cmp_ge_f32_e64 s[18:19], 0, v5
	v_add_u32_e32 v5, 1, v3
	s_nop 0
	v_cndmask_b32_e64 v4, v3, v4, s[18:19]
	v_fma_f32 v3, -v5, v3, v2
	v_cmp_lt_f32_e64 s[18:19], 0, v3
	s_nop 1
	v_cndmask_b32_e64 v3, v4, v5, s[18:19]
	v_mul_f32_e32 v4, 0x37800000, v3
	v_cndmask_b32_e32 v3, v3, v4, vcc
	v_cmp_class_f32_e32 vcc, v2, v186
	s_nop 1
	v_cndmask_b32_e32 v2, v3, v2, vcc
	v_div_scale_f32 v3, s[0:1], v2, v2, 1.0
	v_rcp_f32_e32 v4, v3
	s_nop 0
	v_fma_f32 v5, -v3, v4, 1.0
	v_fmac_f32_e32 v4, v5, v4
	v_div_scale_f32 v5, vcc, 1.0, v2, 1.0
	v_mul_f32_e32 v6, v5, v4
	v_fma_f32 v7, -v3, v6, v5
	v_fmac_f32_e32 v6, v7, v4
	v_fma_f32 v3, -v3, v6, v5
	v_div_fmas_f32 v3, v3, v4, v6
	v_div_fixup_f32 v10, v3, v2, 1.0
.Lhd_one_2:
	v_pk_mul_f32 v[6:7], v[118:119], v[10:11] op_sel_hi:[1,0]
	v_pk_mul_f32 v[8:9], v[120:121], v[10:11] op_sel_hi:[1,0]
	v_pk_mul_f32 v[2:3], v[126:127], v[0:1] op_sel_hi:[1,0]
	v_pk_mul_f32 v[4:5], v[128:129], v[0:1] op_sel_hi:[1,0]
	s_waitcnt vmcnt(0)
	v_pk_mul_f32 v[164:165], v[28:29], v[8:9]
	v_pk_mul_f32 v[162:163], v[26:27], v[6:7]
	v_pk_mul_f32 v[6:7], v[122:123], v[0:1] op_sel_hi:[1,0]
	v_pk_mul_f32 v[8:9], v[124:125], v[0:1] op_sel_hi:[1,0]
	v_pk_mul_f32 v[12:13], v[114:115], v[10:11] op_sel_hi:[1,0]
	v_pk_mul_f32 v[10:11], v[116:117], v[10:11] op_sel_hi:[1,0]
	v_pk_mul_f32 v[4:5], v[32:33], v[4:5]
	v_pk_mul_f32 v[2:3], v[30:31], v[2:3]
	v_pk_mul_f32 v[8:9], v[24:25], v[8:9]
	v_pk_mul_f32 v[6:7], v[22:23], v[6:7]
	v_pk_mul_f32 v[168:169], v[20:21], v[10:11]
	v_pk_mul_f32 v[166:167], v[18:19], v[12:13]
	s_andn2_b64 vcc, exec, s[58:59]
	s_cbranch_vccz .LBB0_603
	s_andn2_b64 vcc, exec, s[74:75]
	s_cbranch_vccz .LBB0_604

;     __device__ __forceinline__ static float xsh(float v, int mask, int lane) { return __builtin_bit_cast(float, __builtin_amdgcn_ds_bpermute((lane ^ mask) << 2, __builtin_bit_cast(int, v))); }
;     __device__ __forceinline__ void head_epilogue(const f32x4 (&acc)[2][2][4][2], const Unit& u, int wr, int wc, int fr, int fq) const {
;     ...
;                     if (cls != 3) { s0 += s1; s0 += xsh(s0, 16, lane); s0 += xsh(s0, 32, lane); s0 = s0 * (1.f / 64.f); s1 = s0; }
;                     else { s0 += xsh(s0, 16, lane); s0 += xsh(s0, 32, lane); s1 += xsh(s1, 16, lane); s1 += xsh(s1, 32, lane); s0 *= (1.f / 32.f); s1 *= (1.f / 32.f); }
;                     const float r0 = 1.f / sqrtf(s0 + 1e-6f), r1 = 1.f / sqrtf(s1 + 1e-6f);
; #pragma unroll
;                     for (int n = 0; n < 2; ++n) { v[0][n] = v[0][n] * r0 * gv[0][n]; v[1][n] = v[1][n] * r1 * gv[1][n]; }
.Lhd_one_3:
	v_pk_mul_f32 v[6:7], v[102:103], v[10:11] op_sel_hi:[1,0]
	v_pk_mul_f32 v[8:9], v[104:105], v[10:11] op_sel_hi:[1,0]
	v_pk_mul_f32 v[2:3], v[110:111], v[0:1] op_sel_hi:[1,0]
	v_pk_mul_f32 v[4:5], v[112:113], v[0:1] op_sel_hi:[1,0]
	s_waitcnt vmcnt(0)
	v_pk_mul_f32 v[164:165], v[28:29], v[8:9]
	v_pk_mul_f32 v[162:163], v[26:27], v[6:7]
	v_pk_mul_f32 v[6:7], v[106:107], v[0:1] op_sel_hi:[1,0]
	v_pk_mul_f32 v[8:9], v[108:109], v[0:1] op_sel_hi:[1,0]
	v_pk_mul_f32 v[12:13], v[98:99], v[10:11] op_sel_hi:[1,0]
	v_pk_mul_f32 v[10:11], v[100:101], v[10:11] op_sel_hi:[1,0]
	v_pk_mul_f32 v[4:5], v[32:33], v[4:5]
	v_pk_mul_f32 v[2:3], v[30:31], v[2:3]
	v_pk_mul_f32 v[8:9], v[24:25], v[8:9]
	v_pk_mul_f32 v[6:7], v[22:23], v[6:7]
	v_pk_mul_f32 v[168:169], v[20:21], v[10:11]
	v_pk_mul_f32 v[166:167], v[18:19], v[12:13]
	s_andn2_b64 vcc, exec, s[58:59]
	s_cbranch_vccz .LBB0_627
	s_andn2_b64 vcc, exec, s[74:75]
	s_cbranch_vccz .LBB0_628

;     __device__ __forceinline__ static float xsh(float v, int mask, int lane) { return __builtin_bit_cast(float, __builtin_amdgcn_ds_bpermute((lane ^ mask) << 2, __builtin_bit_cast(int, v))); }
;     __device__ __forceinline__ void head_epilogue(const f32x4 (&acc)[2][2][4][2], const Unit& u, int wr, int wc, int fr, int fq) const {
;     ...
;                     if (cls != 3) { s0 += s1; s0 += xsh(s0, 16, lane); s0 += xsh(s0, 32, lane); s0 = s0 * (1.f / 64.f); s1 = s0; }
;                     else { s0 += xsh(s0, 16, lane); s0 += xsh(s0, 32, lane); s1 += xsh(s1, 16, lane); s1 += xsh(s1, 32, lane); s0 *= (1.f / 32.f); s1 *= (1.f / 32.f); }
;                     const float r0 = 1.f / sqrtf(s0 + 1e-6f), r1 = 1.f / sqrtf(s1 + 1e-6f);
; #pragma unroll
;                     for (int n = 0; n < 2; ++n) { v[0][n] = v[0][n] * r0 * gv[0][n]; v[1][n] = v[1][n] * r1 * gv[1][n]; }
.Lhd_one_4:
	v_pk_mul_f32 v[6:7], v[86:87], v[10:11] op_sel_hi:[1,0]
	v_pk_mul_f32 v[8:9], v[88:89], v[10:11] op_sel_hi:[1,0]
	v_pk_mul_f32 v[2:3], v[94:95], v[0:1] op_sel_hi:[1,0]
	v_pk_mul_f32 v[4:5], v[96:97], v[0:1] op_sel_hi:[1,0]
	s_waitcnt vmcnt(0)
	v_pk_mul_f32 v[164:165], v[28:29], v[8:9]
	v_pk_mul_f32 v[162:163], v[26:27], v[6:7]
	v_pk_mul_f32 v[6:7], v[90:91], v[0:1] op_sel_hi:[1,0]
	v_pk_mul_f32 v[8:9], v[92:93], v[0:1] op_sel_hi:[1,0]
	v_pk_mul_f32 v[12:13], v[82:83], v[10:11] op_sel_hi:[1,0]
	v_pk_mul_f32 v[10:11], v[84:85], v[10:11] op_sel_hi:[1,0]
	v_pk_mul_f32 v[4:5], v[32:33], v[4:5]
	v_pk_mul_f32 v[2:3], v[30:31], v[2:3]
	v_pk_mul_f32 v[8:9], v[24:25], v[8:9]
	v_pk_mul_f32 v[6:7], v[22:23], v[6:7]
	v_pk_mul_f32 v[168:169], v[20:21], v[10:11]
	v_pk_mul_f32 v[166:167], v[18:19], v[12:13]
	s_andn2_b64 vcc, exec, s[58:59]
	s_cbranch_vccz .LBB0_651
	s_andn2_b64 vcc, exec, s[74:75]
	s_cbranch_vccz .LBB0_652

;     __device__ __forceinline__ static float xsh(float v, int mask, int lane) { return __builtin_bit_cast(float, __builtin_amdgcn_ds_bpermute((lane ^ mask) << 2, __builtin_bit_cast(int, v))); }
;     __device__ __forceinline__ void head_epilogue(const f32x4 (&acc)[2][2][4][2], const Unit& u, int wr, int wc, int fr, int fq) const {
;     ...
;                     if (cls != 3) { s0 += s1; s0 += xsh(s0, 16, lane); s0 += xsh(s0, 32, lane); s0 = s0 * (1.f / 64.f); s1 = s0; }
;                     else { s0 += xsh(s0, 16, lane); s0 += xsh(s0, 32, lane); s1 += xsh(s1, 16, lane); s1 += xsh(s1, 32, lane); s0 *= (1.f / 32.f); s1 *= (1.f / 32.f); }
;                     const float r0 = 1.f / sqrtf(s0 + 1e-6f), r1 = 1.f / sqrtf(s1 + 1e-6f);
; #pragma unroll
;                     for (int n = 0; n < 2; ++n) { v[0][n] = v[0][n] * r0 * gv[0][n]; v[1][n] = v[1][n] * r1 * gv[1][n]; }
.Lhd_one_5:
	v_pk_mul_f32 v[6:7], v[70:71], v[10:11] op_sel_hi:[1,0]
	v_pk_mul_f32 v[8:9], v[72:73], v[10:11] op_sel_hi:[1,0]
	v_pk_mul_f32 v[2:3], v[78:79], v[0:1] op_sel_hi:[1,0]
	v_pk_mul_f32 v[4:5], v[80:81], v[0:1] op_sel_hi:[1,0]
	s_waitcnt vmcnt(0)
	v_pk_mul_f32 v[164:165], v[28:29], v[8:9]
	v_pk_mul_f32 v[162:163], v[26:27], v[6:7]
	v_pk_mul_f32 v[6:7], v[74:75], v[0:1] op_sel_hi:[1,0]
	v_pk_mul_f32 v[8:9], v[76:77], v[0:1] op_sel_hi:[1,0]
	v_pk_mul_f32 v[12:13], v[66:67], v[10:11] op_sel_hi:[1,0]
	v_pk_mul_f32 v[10:11], v[68:69], v[10:11] op_sel_hi:[1,0]
	v_pk_mul_f32 v[4:5], v[32:33], v[4:5]
	v_pk_mul_f32 v[2:3], v[30:31], v[2:3]
	v_pk_mul_f32 v[8:9], v[24:25], v[8:9]
	v_pk_mul_f32 v[6:7], v[22:23], v[6:7]
	v_pk_mul_f32 v[168:169], v[20:21], v[10:11]
	v_pk_mul_f32 v[166:167], v[18:19], v[12:13]
	s_andn2_b64 vcc, exec, s[58:59]
	s_cbranch_vccz .LBB0_675
	s_andn2_b64 vcc, exec, s[74:75]
	s_cbranch_vccz .LBB0_676

;     __device__ __forceinline__ static float xsh(float v, int mask, int lane) { return __builtin_bit_cast(float, __builtin_amdgcn_ds_bpermute((lane ^ mask) << 2, __builtin_bit_cast(int, v))); }
;     __device__ __forceinline__ void head_epilogue(const f32x4 (&acc)[2][2][4][2], const Unit& u, int wr, int wc, int fr, int fq) const {
;     ...
;                     if (cls != 3) { s0 += s1; s0 += xsh(s0, 16, lane); s0 += xsh(s0, 32, lane); s0 = s0 * (1.f / 64.f); s1 = s0; }
;                     else { s0 += xsh(s0, 16, lane); s0 += xsh(s0, 32, lane); s1 += xsh(s1, 16, lane); s1 += xsh(s1, 32, lane); s0 *= (1.f / 32.f); s1 *= (1.f / 32.f); }
;                     const float r0 = 1.f / sqrtf(s0 + 1e-6f), r1 = 1.f / sqrtf(s1 + 1e-6f);
; #pragma unroll
;                     for (int n = 0; n < 2; ++n) { v[0][n] = v[0][n] * r0 * gv[0][n]; v[1][n] = v[1][n] * r1 * gv[1][n]; }
.Lhd_one_6:
	v_pk_mul_f32 v[6:7], v[54:55], v[10:11] op_sel_hi:[1,0]
	v_pk_mul_f32 v[8:9], v[56:57], v[10:11] op_sel_hi:[1,0]
	v_pk_mul_f32 v[2:3], v[62:63], v[0:1] op_sel_hi:[1,0]
	v_pk_mul_f32 v[4:5], v[64:65], v[0:1] op_sel_hi:[1,0]
	s_waitcnt vmcnt(0)
	v_pk_mul_f32 v[164:165], v[28:29], v[8:9]
	v_pk_mul_f32 v[162:163], v[26:27], v[6:7]
	v_pk_mul_f32 v[6:7], v[58:59], v[0:1] op_sel_hi:[1,0]
	v_pk_mul_f32 v[8:9], v[60:61], v[0:1] op_sel_hi:[1,0]
	v_pk_mul_f32 v[12:13], v[50:51], v[10:11] op_sel_hi:[1,0]
	v_pk_mul_f32 v[10:11], v[52:53], v[10:11] op_sel_hi:[1,0]
	v_pk_mul_f32 v[4:5], v[32:33], v[4:5]
	v_pk_mul_f32 v[2:3], v[30:31], v[2:3]
	v_pk_mul_f32 v[8:9], v[24:25], v[8:9]
	v_pk_mul_f32 v[6:7], v[22:23], v[6:7]
	v_pk_mul_f32 v[168:169], v[20:21], v[10:11]
	v_pk_mul_f32 v[166:167], v[18:19], v[12:13]
	s_andn2_b64 vcc, exec, s[58:59]
	s_cbranch_vccz .LBB0_699
	s_andn2_b64 vcc, exec, s[74:75]
	s_cbranch_vccz .LBB0_700

;     __device__ __forceinline__ static float xsh(float v, int mask, int lane) { return __builtin_bit_cast(float, __builtin_amdgcn_ds_bpermute((lane ^ mask) << 2, __builtin_bit_cast(int, v))); }
;     __device__ __forceinline__ void head_epilogue(const f32x4 (&acc)[2][2][4][2], const Unit& u, int wr, int wc, int fr, int fq) const {
;     ...
;                     if (cls != 3) { s0 += s1; s0 += xsh(s0, 16, lane); s0 += xsh(s0, 32, lane); s0 = s0 * (1.f / 64.f); s1 = s0; }
;                     else { s0 += xsh(s0, 16, lane); s0 += xsh(s0, 32, lane); s1 += xsh(s1, 16, lane); s1 += xsh(s1, 32, lane); s0 *= (1.f / 32.f); s1 *= (1.f / 32.f); }
;                     const float r0 = 1.f / sqrtf(s0 + 1e-6f), r1 = 1.f / sqrtf(s1 + 1e-6f);
; #pragma unroll
;                     for (int n = 0; n < 2; ++n) { v[0][n] = v[0][n] * r0 * gv[0][n]; v[1][n] = v[1][n] * r1 * gv[1][n]; }
.LBB0_709:
	s_nop 0
	v_add_f32_e32 v0, 0x358637bd, v3
	s_mov_b32 s14, 0xf800000
	v_cmp_gt_f32_e32 vcc, s14, v0
	v_mul_f32_e32 v3, 0x4f800000, v0
	v_add_f32_e32 v2, 0x358637bd, v2
	v_cndmask_b32_e32 v0, v0, v3, vcc
	v_sqrt_f32_e32 v3, v0
	s_nop 0
	v_add_u32_e32 v4, -1, v3
	v_fma_f32 v5, -v4, v3, v0
	v_cmp_ge_f32_e64 s[0:1], 0, v5
	v_add_u32_e32 v5, 1, v3
	s_nop 0
	v_cndmask_b32_e64 v4, v3, v4, s[0:1]
	v_fma_f32 v3, -v5, v3, v0
	v_cmp_lt_f32_e64 s[0:1], 0, v3
	s_nop 1
	v_cndmask_b32_e64 v3, v4, v5, s[0:1]
	v_mul_f32_e32 v4, 0x37800000, v3
	v_cndmask_b32_e32 v3, v3, v4, vcc
	v_cmp_class_f32_e32 vcc, v0, v186
	s_nop 1
	v_cndmask_b32_e32 v0, v3, v0, vcc
	v_div_scale_f32 v3, s[0:1], v0, v0, 1.0
	v_rcp_f32_e32 v4, v3
	s_nop 0
	v_fma_f32 v5, -v3, v4, 1.0
	v_fmac_f32_e32 v4, v5, v4
	v_div_scale_f32 v5, vcc, 1.0, v0, 1.0
	v_mul_f32_e32 v6, v5, v4
	v_fma_f32 v7, -v3, v6, v5
	v_fmac_f32_e32 v6, v7, v4
	v_fma_f32 v3, -v3, v6, v5
	v_div_fmas_f32 v3, v3, v4, v6
	v_div_fixup_f32 v0, v3, v0, 1.0
	s_and_b64 vcc, exec, s[12:13]
	s_cbranch_vccnz .Lhd_two_7
	v_mov_b32_e32 v10, v0
	s_branch .Lhd_one_7
.Lhd_two_7:
	v_cmp_gt_f32_e32 vcc, s14, v2
	v_mul_f32_e32 v3, 0x4f800000, v2
	s_nop 0
	v_cndmask_b32_e32 v2, v2, v3, vcc
	v_sqrt_f32_e32 v3, v2
	s_nop 0
	v_add_u32_e32 v4, -1, v3
	v_fma_f32 v5, -v4, v3, v2
	v_cmp_ge_f32_e64 s[12:13], 0, v5
	v_add_u32_e32 v5, 1, v3
	s_nop 0
	v_cndmask_b32_e64 v4, v3, v4, s[12:13]
	v_fma_f32 v3, -v5, v3, v2
	v_cmp_lt_f32_e64 s[12:13], 0, v3
	s_nop 1
	v_cndmask_b32_e64 v3, v4, v5, s[12:13]
	v_mul_f32_e32 v4, 0x37800000, v3
	v_cndmask_b32_e32 v3, v3, v4, vcc
	v_cmp_class_f32_e32 vcc, v2, v186
	s_nop 1
	v_cndmask_b32_e32 v2, v3, v2, vcc
	v_div_scale_f32 v3, s[0:1], v2, v2, 1.0
	v_rcp_f32_e32 v4, v3
	s_nop 0
	v_fma_f32 v5, -v3, v4, 1.0
	v_fmac_f32_e32 v4, v5, v4
	v_div_scale_f32 v5, vcc, 1.0, v2, 1.0
	v_mul_f32_e32 v6, v5, v4
	v_fma_f32 v7, -v3, v6, v5
	v_fmac_f32_e32 v6, v7, v4
	v_fma_f32 v3, -v3, v6, v5
	v_div_fmas_f32 v3, v3, v4, v6
	v_div_fixup_f32 v10, v3, v2, 1.0
.Lhd_one_7:
	v_pk_mul_f32 v[6:7], v[38:39], v[10:11] op_sel_hi:[1,0]
	v_pk_mul_f32 v[8:9], v[40:41], v[10:11] op_sel_hi:[1,0]
	v_pk_mul_f32 v[2:3], v[46:47], v[0:1] op_sel_hi:[1,0]
	v_pk_mul_f32 v[4:5], v[48:49], v[0:1] op_sel_hi:[1,0]
	s_waitcnt vmcnt(0)
	v_pk_mul_f32 v[28:29], v[28:29], v[8:9]
	v_pk_mul_f32 v[26:27], v[26:27], v[6:7]
	v_pk_mul_f32 v[6:7], v[42:43], v[0:1] op_sel_hi:[1,0]
	v_pk_mul_f32 v[8:9], v[44:45], v[0:1] op_sel_hi:[1,0]
	v_pk_mul_f32 v[12:13], v[34:35], v[10:11] op_sel_hi:[1,0]
	v_pk_mul_f32 v[10:11], v[36:37], v[10:11] op_sel_hi:[1,0]
	v_pk_mul_f32 v[4:5], v[32:33], v[4:5]
	v_pk_mul_f32 v[2:3], v[30:31], v[2:3]
	v_pk_mul_f32 v[8:9], v[24:25], v[8:9]
	v_pk_mul_f32 v[6:7], v[22:23], v[6:7]
	v_pk_mul_f32 v[20:21], v[20:21], v[10:11]
	v_pk_mul_f32 v[18:19], v[18:19], v[12:13]
	s_andn2_b64 vcc, exec, s[58:59]
	s_cbranch_vccz .LBB0_723
	s_andn2_b64 vcc, exec, s[74:75]
	s_cbranch_vccz .LBB0_724

;     __device__ __forceinline__ static float xsh(float v, int mask, int lane) { return __builtin_bit_cast(float, __builtin_amdgcn_ds_bpermute((lane ^ mask) << 2, __builtin_bit_cast(int, v))); }
;     __device__ __forceinline__ void head_epilogue(const f32x4 (&acc)[2][2][4][2], const Unit& u, int wr, int wc, int fr, int fq) const {
;     ...
;                     if (cls != 3) { s0 += s1; s0 += xsh(s0, 16, lane); s0 += xsh(s0, 32, lane); s0 = s0 * (1.f / 64.f); s1 = s0; }
;                     else { s0 += xsh(s0, 16, lane); s0 += xsh(s0, 32, lane); s1 += xsh(s1, 16, lane); s1 += xsh(s1, 32, lane); s0 *= (1.f / 32.f); s1 *= (1.f / 32.f); }
;                     const float r0 = 1.f / sqrtf(s0 + 1e-6f), r1 = 1.f / sqrtf(s1 + 1e-6f);
; #pragma unroll
;                     for (int n = 0; n < 2; ++n) { v[0][n] = v[0][n] * r0 * gv[0][n]; v[1][n] = v[1][n] * r1 * gv[1][n]; }
.LBB0_867:
	s_nop 0
	v_add_f32_e32 v0, 0x358637bd, v3
	v_cmp_gt_f32_e32 vcc, s64, v0
	v_mul_f32_e32 v3, 0x4f800000, v0
	v_add_f32_e32 v2, 0x358637bd, v2
	v_cndmask_b32_e32 v0, v0, v3, vcc
	v_sqrt_f32_e32 v3, v0
	s_nop 0
	v_add_u32_e32 v4, -1, v3
	v_fma_f32 v5, -v4, v3, v0
	v_cmp_ge_f32_e64 s[12:13], 0, v5
	v_add_u32_e32 v5, 1, v3
	s_nop 0
	v_cndmask_b32_e64 v4, v3, v4, s[12:13]
	v_fma_f32 v3, -v5, v3, v0
	v_cmp_lt_f32_e64 s[12:13], 0, v3
	s_nop 1
	v_cndmask_b32_e64 v3, v4, v5, s[12:13]
	v_mul_f32_e32 v4, 0x37800000, v3
	v_cndmask_b32_e32 v3, v3, v4, vcc
	v_cmp_class_f32_e32 vcc, v0, v186
	s_nop 1
	v_cndmask_b32_e32 v0, v3, v0, vcc
	v_div_scale_f32 v3, s[12:13], v0, v0, 1.0
	v_rcp_f32_e32 v4, v3
	s_nop 0
	v_fma_f32 v5, -v3, v4, 1.0
	v_fmac_f32_e32 v4, v5, v4
	v_div_scale_f32 v5, vcc, 1.0, v0, 1.0
	v_mul_f32_e32 v6, v5, v4
	v_fma_f32 v7, -v3, v6, v5
	v_fmac_f32_e32 v6, v7, v4
	v_fma_f32 v3, -v3, v6, v5
	v_div_fmas_f32 v3, v3, v4, v6
	v_div_fixup_f32 v0, v3, v0, 1.0
	s_and_b64 vcc, exec, s[14:15]
	s_cbranch_vccnz .Lhd_two_8
	v_mov_b32_e32 v10, v0
	s_branch .Lhd_one_8
.Lhd_two_8:
	v_cmp_gt_f32_e32 vcc, s64, v2
	v_mul_f32_e32 v3, 0x4f800000, v2
	s_nop 0
	v_cndmask_b32_e32 v2, v2, v3, vcc
	v_sqrt_f32_e32 v3, v2
	s_nop 0
	v_add_u32_e32 v4, -1, v3
	v_fma_f32 v5, -v4, v3, v2
	v_cmp_ge_f32_e64 s[12:13], 0, v5
	v_add_u32_e32 v5, 1, v3
	s_nop 0
	v_cndmask_b32_e64 v4, v3, v4, s[12:13]
	v_fma_f32 v3, -v5, v3, v2
	v_cmp_lt_f32_e64 s[12:13], 0, v3
	s_nop 1
	v_cndmask_b32_e64 v3, v4, v5, s[12:13]
	v_mul_f32_e32 v4, 0x37800000, v3
	v_cndmask_b32_e32 v3, v3, v4, vcc
	v_cmp_class_f32_e32 vcc, v2, v186
	s_nop 1
	v_cndmask_b32_e32 v2, v3, v2, vcc
	v_div_scale_f32 v3, s[12:13], v2, v2, 1.0
	v_rcp_f32_e32 v4, v3
	s_nop 0
	v_fma_f32 v5, -v3, v4, 1.0
	v_fmac_f32_e32 v4, v5, v4
	v_div_scale_f32 v5, vcc, 1.0, v2, 1.0
	v_mul_f32_e32 v6, v5, v4
	v_fma_f32 v7, -v3, v6, v5
	v_fmac_f32_e32 v6, v7, v4
	v_fma_f32 v3, -v3, v6, v5
	v_div_fmas_f32 v3, v3, v4, v6
	v_div_fixup_f32 v10, v3, v2, 1.0
.Lhd_one_8:
	v_pk_mul_f32 v[6:7], v[134:135], v[10:11] op_sel_hi:[1,0]
	v_pk_mul_f32 v[8:9], v[136:137], v[10:11] op_sel_hi:[1,0]
	v_pk_mul_f32 v[2:3], v[138:139], v[0:1] op_sel_hi:[1,0]
	v_pk_mul_f32 v[4:5], v[140:141], v[0:1] op_sel_hi:[1,0]
	s_waitcnt vmcnt(0)
	v_pk_mul_f32 v[164:165], v[156:157], v[8:9]
	v_pk_mul_f32 v[162:163], v[154:155], v[6:7]
	v_pk_mul_f32 v[6:7], v[142:143], v[0:1] op_sel_hi:[1,0]
	v_pk_mul_f32 v[8:9], v[144:145], v[0:1] op_sel_hi:[1,0]
	v_pk_mul_f32 v[12:13], v[130:131], v[10:11] op_sel_hi:[1,0]
	v_pk_mul_f32 v[10:11], v[132:133], v[10:11] op_sel_hi:[1,0]
	v_pk_mul_f32 v[4:5], v[160:161], v[4:5]
	v_pk_mul_f32 v[2:3], v[158:159], v[2:3]
	v_pk_mul_f32 v[8:9], v[152:153], v[8:9]
	v_pk_mul_f32 v[6:7], v[150:151], v[6:7]
	v_pk_mul_f32 v[168:169], v[148:149], v[10:11]
	v_pk_mul_f32 v[166:167], v[146:147], v[12:13]
	s_andn2_b64 vcc, exec, s[58:59]
	s_cbranch_vccz .LBB0_871
	s_andn2_b64 vcc, exec, s[74:75]
	s_cbranch_vccz .LBB0_872

;     __device__ __forceinline__ static float xsh(float v, int mask, int lane) { return __builtin_bit_cast(float, __builtin_amdgcn_ds_bpermute((lane ^ mask) << 2, __builtin_bit_cast(int, v))); }
;     __device__ __forceinline__ void head_epilogue(const f32x4 (&acc)[2][2][4][2], const Unit& u, int wr, int wc, int fr, int fq) const {
;     ...
;                     if (cls != 3) { s0 += s1; s0 += xsh(s0, 16, lane); s0 += xsh(s0, 32, lane); s0 = s0 * (1.f / 64.f); s1 = s0; }
;                     else { s0 += xsh(s0, 16, lane); s0 += xsh(s0, 32, lane); s1 += xsh(s1, 16, lane); s1 += xsh(s1, 32, lane); s0 *= (1.f / 32.f); s1 *= (1.f / 32.f); }
;                     const float r0 = 1.f / sqrtf(s0 + 1e-6f), r1 = 1.f / sqrtf(s1 + 1e-6f);
; #pragma unroll
;                     for (int n = 0; n < 2; ++n) { v[0][n] = v[0][n] * r0 * gv[0][n]; v[1][n] = v[1][n] * r1 * gv[1][n]; }
.LBB0_891:
	s_nop 0
	v_add_f32_e32 v0, 0x358637bd, v3
	s_mov_b32 s20, 0xf800000
	v_cmp_gt_f32_e32 vcc, s20, v0
	v_mul_f32_e32 v3, 0x4f800000, v0
	v_add_f32_e32 v2, 0x358637bd, v2
	v_cndmask_b32_e32 v0, v0, v3, vcc
	v_sqrt_f32_e32 v3, v0
	s_nop 0
	v_add_u32_e32 v4, -1, v3
	v_fma_f32 v5, -v4, v3, v0
	v_cmp_ge_f32_e64 s[18:19], 0, v5
	v_add_u32_e32 v5, 1, v3
	s_nop 0
	v_cndmask_b32_e64 v4, v3, v4, s[18:19]
	v_fma_f32 v3, -v5, v3, v0
	v_cmp_lt_f32_e64 s[18:19], 0, v3
	s_nop 1
	v_cndmask_b32_e64 v3, v4, v5, s[18:19]
	v_mul_f32_e32 v4, 0x37800000, v3
	v_cndmask_b32_e32 v3, v3, v4, vcc
	v_cmp_class_f32_e32 vcc, v0, v186
	s_nop 1
	v_cndmask_b32_e32 v0, v3, v0, vcc
	v_div_scale_f32 v3, s[18:19], v0, v0, 1.0
	v_rcp_f32_e32 v4, v3
	s_nop 0
	v_fma_f32 v5, -v3, v4, 1.0
	v_fmac_f32_e32 v4, v5, v4
	v_div_scale_f32 v5, vcc, 1.0, v0, 1.0
	v_mul_f32_e32 v6, v5, v4
	v_fma_f32 v7, -v3, v6, v5
	v_fmac_f32_e32 v6, v7, v4
	v_fma_f32 v3, -v3, v6, v5
	v_div_fmas_f32 v3, v3, v4, v6
	v_div_fixup_f32 v0, v3, v0, 1.0
	s_and_b64 vcc, exec, s[14:15]
	s_cbranch_vccnz .Lhd_two_9
	v_mov_b32_e32 v10, v0
	s_branch .Lhd_one_9
.Lhd_two_9:
	v_cmp_gt_f32_e32 vcc, s20, v2
	v_mul_f32_e32 v3, 0x4f800000, v2
	s_nop 0
	v_cndmask_b32_e32 v2, v2, v3, vcc
	v_sqrt_f32_e32 v3, v2
	s_nop 0
	v_add_u32_e32 v4, -1, v3
	v_fma_f32 v5, -v4, v3, v2
	v_cmp_ge_f32_e64 s[18:19], 0, v5
	v_add_u32_e32 v5, 1, v3
	s_nop 0
	v_cndmask_b32_e64 v4, v3, v4, s[18:19]
	v_fma_f32 v3, -v5, v3, v2
	v_cmp_lt_f32_e64 s[18:19], 0, v3
	s_nop 1
	v_cndmask_b32_e64 v3, v4, v5, s[18:19]
	v_mul_f32_e32 v4, 0x37800000, v3
	v_cndmask_b32_e32 v3, v3, v4, vcc
	v_cmp_class_f32_e32 vcc, v2, v186
	s_nop 1
	v_cndmask_b32_e32 v2, v3, v2, vcc
	v_div_scale_f32 v3, s[18:19], v2, v2, 1.0
	v_rcp_f32_e32 v4, v3
	s_nop 0
	v_fma_f32 v5, -v3, v4, 1.0
	v_fmac_f32_e32 v4, v5, v4
	v_div_scale_f32 v5, vcc, 1.0, v2, 1.0
	v_mul_f32_e32 v6, v5, v4
	v_fma_f32 v7, -v3, v6, v5
	v_fmac_f32_e32 v6, v7, v4
	v_fma_f32 v3, -v3, v6, v5
	v_div_fmas_f32 v3, v3, v4, v6
	v_div_fixup_f32 v10, v3, v2, 1.0
.Lhd_one_9:
	v_pk_mul_f32 v[6:7], v[118:119], v[10:11] op_sel_hi:[1,0]
	v_pk_mul_f32 v[8:9], v[120:121], v[10:11] op_sel_hi:[1,0]
	v_pk_mul_f32 v[2:3], v[126:127], v[0:1] op_sel_hi:[1,0]
	v_pk_mul_f32 v[4:5], v[128:129], v[0:1] op_sel_hi:[1,0]
	s_waitcnt vmcnt(0)
	v_pk_mul_f32 v[164:165], v[156:157], v[8:9]
	v_pk_mul_f32 v[162:163], v[154:155], v[6:7]
	v_pk_mul_f32 v[6:7], v[122:123], v[0:1] op_sel_hi:[1,0]
	v_pk_mul_f32 v[8:9], v[124:125], v[0:1] op_sel_hi:[1,0]
	v_pk_mul_f32 v[12:13], v[114:115], v[10:11] op_sel_hi:[1,0]
	v_pk_mul_f32 v[10:11], v[116:117], v[10:11] op_sel_hi:[1,0]
	v_pk_mul_f32 v[4:5], v[160:161], v[4:5]
	v_pk_mul_f32 v[2:3], v[158:159], v[2:3]
	v_pk_mul_f32 v[8:9], v[152:153], v[8:9]
	v_pk_mul_f32 v[6:7], v[150:151], v[6:7]
	v_pk_mul_f32 v[168:169], v[148:149], v[10:11]
	v_pk_mul_f32 v[166:167], v[146:147], v[12:13]
	s_andn2_b64 vcc, exec, s[58:59]
	s_cbranch_vccz .LBB0_895
	s_andn2_b64 vcc, exec, s[74:75]
	s_cbranch_vccz .LBB0_896

;     __device__ __forceinline__ static float xsh(float v, int mask, int lane) { return __builtin_bit_cast(float, __builtin_amdgcn_ds_bpermute((lane ^ mask) << 2, __builtin_bit_cast(int, v))); }
;     __device__ __forceinline__ void head_epilogue(const f32x4 (&acc)[2][2][4][2], const Unit& u, int wr, int wc, int fr, int fq) const {
;     ...
;                     if (cls != 3) { s0 += s1; s0 += xsh(s0, 16, lane); s0 += xsh(s0, 32, lane); s0 = s0 * (1.f / 64.f); s1 = s0; }
;                     else { s0 += xsh(s0, 16, lane); s0 += xsh(s0, 32, lane); s1 += xsh(s1, 16, lane); s1 += xsh(s1, 32, lane); s0 *= (1.f / 32.f); s1 *= (1.f / 32.f); }
;                     const float r0 = 1.f / sqrtf(s0 + 1e-6f), r1 = 1.f / sqrtf(s1 + 1e-6f);
; #pragma unroll
;                     for (int n = 0; n < 2; ++n) { v[0][n] = v[0][n] * r0 * gv[0][n]; v[1][n] = v[1][n] * r1 * gv[1][n]; }
.LBB0_905:
	s_nop 0
	v_add_f32_e32 v0, 0x358637bd, v3
	s_mov_b32 s4, 0xf800000
	v_cmp_gt_f32_e32 vcc, s4, v0
	v_mul_f32_e32 v3, 0x4f800000, v0
	v_add_f32_e32 v2, 0x358637bd, v2
	v_cndmask_b32_e32 v0, v0, v3, vcc
	v_sqrt_f32_e32 v3, v0
	s_nop 0
	v_add_u32_e32 v4, -1, v3
	v_fma_f32 v5, -v4, v3, v0
	v_cmp_ge_f32_e64 s[20:21], 0, v5
	v_add_u32_e32 v5, 1, v3
	s_nop 0
	v_cndmask_b32_e64 v4, v3, v4, s[20:21]
	v_fma_f32 v3, -v5, v3, v0
	v_cmp_lt_f32_e64 s[20:21], 0, v3
	s_nop 1
	v_cndmask_b32_e64 v3, v4, v5, s[20:21]
	v_mul_f32_e32 v4, 0x37800000, v3
	v_cndmask_b32_e32 v3, v3, v4, vcc
	v_cmp_class_f32_e32 vcc, v0, v186
	s_nop 1
	v_cndmask_b32_e32 v0, v3, v0, vcc
	v_div_scale_f32 v3, s[0:1], v0, v0, 1.0
	v_rcp_f32_e32 v4, v3
	s_nop 0
	v_fma_f32 v5, -v3, v4, 1.0
	v_fmac_f32_e32 v4, v5, v4
	v_div_scale_f32 v5, vcc, 1.0, v0, 1.0
	v_mul_f32_e32 v6, v5, v4
	v_fma_f32 v7, -v3, v6, v5
	v_fmac_f32_e32 v6, v7, v4
	v_fma_f32 v3, -v3, v6, v5
	v_div_fmas_f32 v3, v3, v4, v6
	v_div_fixup_f32 v0, v3, v0, 1.0
	s_and_b64 vcc, exec, s[14:15]
	s_cbranch_vccnz .Lhd_two_10
	v_mov_b32_e32 v10, v0
	s_branch .Lhd_one_10
.Lhd_two_10:
	v_cmp_gt_f32_e32 vcc, s4, v2
	v_mul_f32_e32 v3, 0x4f800000, v2
	s_nop 0
	v_cndmask_b32_e32 v2, v2, v3, vcc
	v_sqrt_f32_e32 v3, v2
	s_nop 0
	v_add_u32_e32 v4, -1, v3
	v_fma_f32 v5, -v4, v3, v2
	v_cmp_ge_f32_e64 s[20:21], 0, v5
	v_add_u32_e32 v5, 1, v3
	s_nop 0
	v_cndmask_b32_e64 v4, v3, v4, s[20:21]
	v_fma_f32 v3, -v5, v3, v2
	v_cmp_lt_f32_e64 s[20:21], 0, v3
	s_nop 1
	v_cndmask_b32_e64 v3, v4, v5, s[20:21]
	v_mul_f32_e32 v4, 0x37800000, v3
	v_cndmask_b32_e32 v3, v3, v4, vcc
	v_cmp_class_f32_e32 vcc, v2, v186
	s_nop 1
	v_cndmask_b32_e32 v2, v3, v2, vcc
	v_div_scale_f32 v3, s[0:1], v2, v2, 1.0
	v_rcp_f32_e32 v4, v3
	s_nop 0
	v_fma_f32 v5, -v3, v4, 1.0
	v_fmac_f32_e32 v4, v5, v4
	v_div_scale_f32 v5, vcc, 1.0, v2, 1.0
	v_mul_f32_e32 v6, v5, v4
	v_fma_f32 v7, -v3, v6, v5
	v_fmac_f32_e32 v6, v7, v4
	v_fma_f32 v3, -v3, v6, v5
	v_div_fmas_f32 v3, v3, v4, v6
	v_div_fixup_f32 v10, v3, v2, 1.0
.Lhd_one_10:
	v_pk_mul_f32 v[6:7], v[102:103], v[10:11] op_sel_hi:[1,0]
	v_pk_mul_f32 v[8:9], v[104:105], v[10:11] op_sel_hi:[1,0]
	v_pk_mul_f32 v[2:3], v[110:111], v[0:1] op_sel_hi:[1,0]
	v_pk_mul_f32 v[4:5], v[112:113], v[0:1] op_sel_hi:[1,0]
	s_waitcnt vmcnt(0)
	v_pk_mul_f32 v[164:165], v[156:157], v[8:9]
	v_pk_mul_f32 v[162:163], v[154:155], v[6:7]
	v_pk_mul_f32 v[6:7], v[106:107], v[0:1] op_sel_hi:[1,0]
	v_pk_mul_f32 v[8:9], v[108:109], v[0:1] op_sel_hi:[1,0]
	v_pk_mul_f32 v[12:13], v[98:99], v[10:11] op_sel_hi:[1,0]
	v_pk_mul_f32 v[10:11], v[100:101], v[10:11] op_sel_hi:[1,0]
	v_pk_mul_f32 v[4:5], v[160:161], v[4:5]
	v_pk_mul_f32 v[2:3], v[158:159], v[2:3]
	v_pk_mul_f32 v[8:9], v[152:153], v[8:9]
	v_pk_mul_f32 v[6:7], v[150:151], v[6:7]
	v_pk_mul_f32 v[168:169], v[148:149], v[10:11]
	v_pk_mul_f32 v[166:167], v[146:147], v[12:13]
	s_andn2_b64 vcc, exec, s[58:59]
	s_cbranch_vccz .LBB0_919
	s_andn2_b64 vcc, exec, s[74:75]
	s_cbranch_vccz .LBB0_920

;     __device__ __forceinline__ static float xsh(float v, int mask, int lane) { return __builtin_bit_cast(float, __builtin_amdgcn_ds_bpermute((lane ^ mask) << 2, __builtin_bit_cast(int, v))); }
;     __device__ __forceinline__ void head_epilogue(const f32x4 (&acc)[2][2][4][2], const Unit& u, int wr, int wc, int fr, int fq) const {
;     ...
;                     if (cls != 3) { s0 += s1; s0 += xsh(s0, 16, lane); s0 += xsh(s0, 32, lane); s0 = s0 * (1.f / 64.f); s1 = s0; }
;                     else { s0 += xsh(s0, 16, lane); s0 += xsh(s0, 32, lane); s1 += xsh(s1, 16, lane); s1 += xsh(s1, 32, lane); s0 *= (1.f / 32.f); s1 *= (1.f / 32.f); }
;                     const float r0 = 1.f / sqrtf(s0 + 1e-6f), r1 = 1.f / sqrtf(s1 + 1e-6f);
; #pragma unroll
;                     for (int n = 0; n < 2; ++n) { v[0][n] = v[0][n] * r0 * gv[0][n]; v[1][n] = v[1][n] * r1 * gv[1][n]; }
.Lhd_one_11:
	v_pk_mul_f32 v[6:7], v[86:87], v[10:11] op_sel_hi:[1,0]
	v_pk_mul_f32 v[8:9], v[88:89], v[10:11] op_sel_hi:[1,0]
	v_pk_mul_f32 v[2:3], v[94:95], v[0:1] op_sel_hi:[1,0]
	v_pk_mul_f32 v[4:5], v[96:97], v[0:1] op_sel_hi:[1,0]
	s_waitcnt vmcnt(0)
	v_pk_mul_f32 v[164:165], v[156:157], v[8:9]
	v_pk_mul_f32 v[162:163], v[154:155], v[6:7]
	v_pk_mul_f32 v[6:7], v[90:91], v[0:1] op_sel_hi:[1,0]
	v_pk_mul_f32 v[8:9], v[92:93], v[0:1] op_sel_hi:[1,0]
	v_pk_mul_f32 v[12:13], v[82:83], v[10:11] op_sel_hi:[1,0]
	v_pk_mul_f32 v[10:11], v[84:85], v[10:11] op_sel_hi:[1,0]
	v_pk_mul_f32 v[4:5], v[160:161], v[4:5]
	v_pk_mul_f32 v[2:3], v[158:159], v[2:3]
	v_pk_mul_f32 v[8:9], v[152:153], v[8:9]
	v_pk_mul_f32 v[6:7], v[150:151], v[6:7]
	v_pk_mul_f32 v[168:169], v[148:149], v[10:11]
	v_pk_mul_f32 v[166:167], v[146:147], v[12:13]
	s_andn2_b64 vcc, exec, s[58:59]
	s_cbranch_vccz .LBB0_943
	s_andn2_b64 vcc, exec, s[74:75]
	s_cbranch_vccz .LBB0_944

;     __device__ __forceinline__ static float xsh(float v, int mask, int lane) { return __builtin_bit_cast(float, __builtin_amdgcn_ds_bpermute((lane ^ mask) << 2, __builtin_bit_cast(int, v))); }
;     __device__ __forceinline__ void head_epilogue(const f32x4 (&acc)[2][2][4][2], const Unit& u, int wr, int wc, int fr, int fq) const {
;     ...
;                     if (cls != 3) { s0 += s1; s0 += xsh(s0, 16, lane); s0 += xsh(s0, 32, lane); s0 = s0 * (1.f / 64.f); s1 = s0; }
;                     else { s0 += xsh(s0, 16, lane); s0 += xsh(s0, 32, lane); s1 += xsh(s1, 16, lane); s1 += xsh(s1, 32, lane); s0 *= (1.f / 32.f); s1 *= (1.f / 32.f); }
;                     const float r0 = 1.f / sqrtf(s0 + 1e-6f), r1 = 1.f / sqrtf(s1 + 1e-6f);
; #pragma unroll
;                     for (int n = 0; n < 2; ++n) { v[0][n] = v[0][n] * r0 * gv[0][n]; v[1][n] = v[1][n] * r1 * gv[1][n]; }
.Lhd_one_12:
	v_pk_mul_f32 v[6:7], v[70:71], v[10:11] op_sel_hi:[1,0]
	v_pk_mul_f32 v[8:9], v[72:73], v[10:11] op_sel_hi:[1,0]
	v_pk_mul_f32 v[2:3], v[78:79], v[0:1] op_sel_hi:[1,0]
	v_pk_mul_f32 v[4:5], v[80:81], v[0:1] op_sel_hi:[1,0]
	s_waitcnt vmcnt(0)
	v_pk_mul_f32 v[164:165], v[156:157], v[8:9]
	v_pk_mul_f32 v[162:163], v[154:155], v[6:7]
	v_pk_mul_f32 v[6:7], v[74:75], v[0:1] op_sel_hi:[1,0]
	v_pk_mul_f32 v[8:9], v[76:77], v[0:1] op_sel_hi:[1,0]
	v_pk_mul_f32 v[12:13], v[66:67], v[10:11] op_sel_hi:[1,0]
	v_pk_mul_f32 v[10:11], v[68:69], v[10:11] op_sel_hi:[1,0]
	v_pk_mul_f32 v[4:5], v[160:161], v[4:5]
	v_pk_mul_f32 v[2:3], v[158:159], v[2:3]
	v_pk_mul_f32 v[8:9], v[152:153], v[8:9]
	v_pk_mul_f32 v[6:7], v[150:151], v[6:7]
	v_pk_mul_f32 v[168:169], v[148:149], v[10:11]
	v_pk_mul_f32 v[166:167], v[146:147], v[12:13]
	s_andn2_b64 vcc, exec, s[58:59]
	s_cbranch_vccz .LBB0_967
	s_andn2_b64 vcc, exec, s[74:75]
	s_cbranch_vccz .LBB0_968

;     __device__ __forceinline__ static float xsh(float v, int mask, int lane) { return __builtin_bit_cast(float, __builtin_amdgcn_ds_bpermute((lane ^ mask) << 2, __builtin_bit_cast(int, v))); }
;     __device__ __forceinline__ void head_epilogue(const f32x4 (&acc)[2][2][4][2], const Unit& u, int wr, int wc, int fr, int fq) const {
;     ...
;                     if (cls != 3) { s0 += s1; s0 += xsh(s0, 16, lane); s0 += xsh(s0, 32, lane); s0 = s0 * (1.f / 64.f); s1 = s0; }
;                     else { s0 += xsh(s0, 16, lane); s0 += xsh(s0, 32, lane); s1 += xsh(s1, 16, lane); s1 += xsh(s1, 32, lane); s0 *= (1.f / 32.f); s1 *= (1.f / 32.f); }
;                     const float r0 = 1.f / sqrtf(s0 + 1e-6f), r1 = 1.f / sqrtf(s1 + 1e-6f);
; #pragma unroll
;                     for (int n = 0; n < 2; ++n) { v[0][n] = v[0][n] * r0 * gv[0][n]; v[1][n] = v[1][n] * r1 * gv[1][n]; }
.Lhd_one_13:
	v_pk_mul_f32 v[6:7], v[54:55], v[10:11] op_sel_hi:[1,0]
	v_pk_mul_f32 v[8:9], v[56:57], v[10:11] op_sel_hi:[1,0]
	v_pk_mul_f32 v[2:3], v[62:63], v[0:1] op_sel_hi:[1,0]
	v_pk_mul_f32 v[4:5], v[64:65], v[0:1] op_sel_hi:[1,0]
	s_waitcnt vmcnt(0)
	v_pk_mul_f32 v[164:165], v[156:157], v[8:9]
	v_pk_mul_f32 v[162:163], v[154:155], v[6:7]
	v_pk_mul_f32 v[6:7], v[58:59], v[0:1] op_sel_hi:[1,0]
	v_pk_mul_f32 v[8:9], v[60:61], v[0:1] op_sel_hi:[1,0]
	v_pk_mul_f32 v[12:13], v[50:51], v[10:11] op_sel_hi:[1,0]
	v_pk_mul_f32 v[10:11], v[52:53], v[10:11] op_sel_hi:[1,0]
	v_pk_mul_f32 v[4:5], v[160:161], v[4:5]
	v_pk_mul_f32 v[2:3], v[158:159], v[2:3]
	v_pk_mul_f32 v[8:9], v[152:153], v[8:9]
	v_pk_mul_f32 v[6:7], v[150:151], v[6:7]
	v_pk_mul_f32 v[168:169], v[148:149], v[10:11]
	v_pk_mul_f32 v[166:167], v[146:147], v[12:13]
	s_andn2_b64 vcc, exec, s[58:59]
	s_cbranch_vccz .LBB0_991
	s_andn2_b64 vcc, exec, s[74:75]
	s_cbranch_vccz .LBB0_992

;     __device__ __forceinline__ static float xsh(float v, int mask, int lane) { return __builtin_bit_cast(float, __builtin_amdgcn_ds_bpermute((lane ^ mask) << 2, __builtin_bit_cast(int, v))); }
;     __device__ __forceinline__ void head_epilogue(const f32x4 (&acc)[2][2][4][2], const Unit& u, int wr, int wc, int fr, int fq) const {
;     ...
;                     if (cls != 3) { s0 += s1; s0 += xsh(s0, 16, lane); s0 += xsh(s0, 32, lane); s0 = s0 * (1.f / 64.f); s1 = s0; }
;                     else { s0 += xsh(s0, 16, lane); s0 += xsh(s0, 32, lane); s1 += xsh(s1, 16, lane); s1 += xsh(s1, 32, lane); s0 *= (1.f / 32.f); s1 *= (1.f / 32.f); }
;                     const float r0 = 1.f / sqrtf(s0 + 1e-6f), r1 = 1.f / sqrtf(s1 + 1e-6f);
; #pragma unroll
;                     for (int n = 0; n < 2; ++n) { v[0][n] = v[0][n] * r0 * gv[0][n]; v[1][n] = v[1][n] * r1 * gv[1][n]; }
.Lhd_one_14:
	v_pk_mul_f32 v[6:7], v[38:39], v[10:11] op_sel_hi:[1,0]
	v_pk_mul_f32 v[8:9], v[40:41], v[10:11] op_sel_hi:[1,0]
	v_pk_mul_f32 v[2:3], v[46:47], v[0:1] op_sel_hi:[1,0]
	v_pk_mul_f32 v[4:5], v[48:49], v[0:1] op_sel_hi:[1,0]
	s_waitcnt vmcnt(0)
	v_pk_mul_f32 v[164:165], v[156:157], v[8:9]
	v_pk_mul_f32 v[162:163], v[154:155], v[6:7]
	v_pk_mul_f32 v[6:7], v[42:43], v[0:1] op_sel_hi:[1,0]
	v_pk_mul_f32 v[8:9], v[44:45], v[0:1] op_sel_hi:[1,0]
	v_pk_mul_f32 v[12:13], v[34:35], v[10:11] op_sel_hi:[1,0]
	v_pk_mul_f32 v[10:11], v[36:37], v[10:11] op_sel_hi:[1,0]
	v_pk_mul_f32 v[4:5], v[160:161], v[4:5]
	v_pk_mul_f32 v[2:3], v[158:159], v[2:3]
	v_pk_mul_f32 v[8:9], v[152:153], v[8:9]
	v_pk_mul_f32 v[6:7], v[150:151], v[6:7]
	v_pk_mul_f32 v[168:169], v[148:149], v[10:11]
	v_pk_mul_f32 v[166:167], v[146:147], v[12:13]
	s_andn2_b64 vcc, exec, s[58:59]
	s_cbranch_vccz .LBB0_1015
	s_andn2_b64 vcc, exec, s[74:75]
	s_cbranch_vccz .LBB0_1016

;     __device__ __forceinline__ static float xsh(float v, int mask, int lane) { return __builtin_bit_cast(float, __builtin_amdgcn_ds_bpermute((lane ^ mask) << 2, __builtin_bit_cast(int, v))); }
;     __device__ __forceinline__ void head_epilogue(const f32x4 (&acc)[2][2][4][2], const Unit& u, int wr, int wc, int fr, int fq) const {
;     ...
;                     if (cls != 3) { s0 += s1; s0 += xsh(s0, 16, lane); s0 += xsh(s0, 32, lane); s0 = s0 * (1.f / 64.f); s1 = s0; }
;                     else { s0 += xsh(s0, 16, lane); s0 += xsh(s0, 32, lane); s1 += xsh(s1, 16, lane); s1 += xsh(s1, 32, lane); s0 *= (1.f / 32.f); s1 *= (1.f / 32.f); }
;                     const float r0 = 1.f / sqrtf(s0 + 1e-6f), r1 = 1.f / sqrtf(s1 + 1e-6f);
; #pragma unroll
;                     for (int n = 0; n < 2; ++n) { v[0][n] = v[0][n] * r0 * gv[0][n]; v[1][n] = v[1][n] * r1 * gv[1][n]; }
.LBB0_1025:
	s_nop 0
	v_add_f32_e32 v0, 0x358637bd, v3
	s_mov_b32 s4, 0xf800000
	v_cmp_gt_f32_e32 vcc, s4, v0
	v_mul_f32_e32 v3, 0x4f800000, v0
	v_add_f32_e32 v2, 0x358637bd, v2
	v_cndmask_b32_e32 v0, v0, v3, vcc
	v_sqrt_f32_e32 v3, v0
	s_nop 0
	v_add_u32_e32 v4, -1, v3
	v_fma_f32 v5, -v4, v3, v0
	v_cmp_ge_f32_e64 s[0:1], 0, v5
	v_add_u32_e32 v5, 1, v3
	s_nop 0
	v_cndmask_b32_e64 v4, v3, v4, s[0:1]
	v_fma_f32 v3, -v5, v3, v0
	v_cmp_lt_f32_e64 s[0:1], 0, v3
	s_nop 1
	v_cndmask_b32_e64 v3, v4, v5, s[0:1]
	v_mul_f32_e32 v4, 0x37800000, v3
	v_cndmask_b32_e32 v3, v3, v4, vcc
	v_cmp_class_f32_e32 vcc, v0, v186
	s_nop 1
	v_cndmask_b32_e32 v0, v3, v0, vcc
	v_div_scale_f32 v3, s[0:1], v0, v0, 1.0
	v_rcp_f32_e32 v4, v3
	s_nop 0
	v_fma_f32 v5, -v3, v4, 1.0
	v_fmac_f32_e32 v4, v5, v4
	v_div_scale_f32 v5, vcc, 1.0, v0, 1.0
	v_mul_f32_e32 v6, v5, v4
	v_fma_f32 v7, -v3, v6, v5
	v_fmac_f32_e32 v6, v7, v4
	v_fma_f32 v3, -v3, v6, v5
	v_div_fmas_f32 v3, v3, v4, v6
	v_div_fixup_f32 v0, v3, v0, 1.0
	s_and_b64 vcc, exec, s[14:15]
	s_cbranch_vccnz .Lhd_two_15
	v_mov_b32_e32 v10, v0
	s_branch .Lhd_one_15
.Lhd_two_15:
	v_cmp_gt_f32_e32 vcc, s4, v2
	v_mul_f32_e32 v3, 0x4f800000, v2
	s_nop 0
	v_cndmask_b32_e32 v2, v2, v3, vcc
	v_sqrt_f32_e32 v3, v2
	s_nop 0
	v_add_u32_e32 v4, -1, v3
	v_fma_f32 v5, -v4, v3, v2
	v_cmp_ge_f32_e64 s[14:15], 0, v5
	v_add_u32_e32 v5, 1, v3
	s_nop 0
	v_cndmask_b32_e64 v4, v3, v4, s[14:15]
	v_fma_f32 v3, -v5, v3, v2
	v_cmp_lt_f32_e64 s[14:15], 0, v3
	s_nop 1
	v_cndmask_b32_e64 v3, v4, v5, s[14:15]
	v_mul_f32_e32 v4, 0x37800000, v3
	v_cndmask_b32_e32 v3, v3, v4, vcc
	v_cmp_class_f32_e32 vcc, v2, v186
	s_nop 1
	v_cndmask_b32_e32 v2, v3, v2, vcc
	v_div_scale_f32 v3, s[0:1], v2, v2, 1.0
	v_rcp_f32_e32 v4, v3
	s_nop 0
	v_fma_f32 v5, -v3, v4, 1.0
	v_fmac_f32_e32 v4, v5, v4
	v_div_scale_f32 v5, vcc, 1.0, v2, 1.0
	v_mul_f32_e32 v6, v5, v4
	v_fma_f32 v7, -v3, v6, v5
	v_fmac_f32_e32 v6, v7, v4
	v_fma_f32 v3, -v3, v6, v5
	v_div_fmas_f32 v3, v3, v4, v6
	v_div_fixup_f32 v10, v3, v2, 1.0
.Lhd_one_15:
	v_pk_mul_f32 v[6:7], v[22:23], v[10:11] op_sel_hi:[1,0]
	v_pk_mul_f32 v[8:9], v[24:25], v[10:11] op_sel_hi:[1,0]
	v_pk_mul_f32 v[2:3], v[30:31], v[0:1] op_sel_hi:[1,0]
	v_pk_mul_f32 v[4:5], v[32:33], v[0:1] op_sel_hi:[1,0]
	s_waitcnt vmcnt(0)
	v_pk_mul_f32 v[156:157], v[156:157], v[8:9]
	v_pk_mul_f32 v[154:155], v[154:155], v[6:7]
	v_pk_mul_f32 v[6:7], v[26:27], v[0:1] op_sel_hi:[1,0]
	v_pk_mul_f32 v[8:9], v[28:29], v[0:1] op_sel_hi:[1,0]
	v_pk_mul_f32 v[12:13], v[18:19], v[10:11] op_sel_hi:[1,0]
	v_pk_mul_f32 v[10:11], v[20:21], v[10:11] op_sel_hi:[1,0]
	v_pk_mul_f32 v[4:5], v[160:161], v[4:5]
	v_pk_mul_f32 v[2:3], v[158:159], v[2:3]
	v_pk_mul_f32 v[8:9], v[152:153], v[8:9]
	v_pk_mul_f32 v[6:7], v[150:151], v[6:7]
	v_pk_mul_f32 v[148:149], v[148:149], v[10:11]
	v_pk_mul_f32 v[146:147], v[146:147], v[12:13]
	s_andn2_b64 vcc, exec, s[58:59]
	s_cbranch_vccz .LBB0_1039
	s_andn2_b64 vcc, exec, s[74:75]
	s_cbranch_vccz .LBB0_1040
